# EpiIn pn=36 (k_pe rope) tiles: per-row COS/SIN vectors prefetched 4 rows ahead into a register pool, replacing 8 load+vmcnt(0) round trips on the tail round
# baseline (speedup 1.0000x reference)
; #define PG8_STAGE(bufoff, gbase, voff) do { _Pragma("unroll") for (int _i = 0; _i < 2; ++_i) \
;         __builtin_amdgcn_global_load_lds((const unsigned*)((const char*)(gbase) + (voff)[_i]), (LAS unsigned*)(lds + (bufoff) + ldsw + _i * 8192), 16, 0, 0); } while (0)
; #define PG8_LDA(dst, b, h) do { _Pragma("unroll") for (int m = 0; m < 4; ++m) _Pragma("unroll") for (int k = 0; k < 2; ++k) dst[m][k] = *(const LAS bf16x8*)(lds + PG8_SA(b, h) + aoff + m * 2048 + k * 1024); } while (0)
; #define PG8_LDB(dst, b, h) do { _Pragma("unroll") for (int n = 0; n < 2; ++n) _Pragma("unroll") for (int k = 0; k < 2; ++k) dst[n][k] = *(const LAS bf16x8*)(lds + PG8_SB(b, h) + boff + n * 2048 + k * 1024); } while (0)
; #define PG8_MMA(ai, bj, At, Bt) do { __builtin_amdgcn_s_setprio(1); _Pragma("unroll") for (int m = 0; m < 4; ++m) _Pragma("unroll") for (int n = 0; n < 2; ++n) _Pragma("unroll") for (int k = 0; k < 2; ++k) \
;         acc[ai][bj][m][n] = __builtin_amdgcn_mfma_f32_16x16x32_bf16(Bt[n][k], At[m][k], acc[ai][bj][m][n], 0, 0, 0); __builtin_amdgcn_s_setprio(0); } while (0)
; template <class Epi>
; __device__ __forceinline__ void gemm_phase(LAS unsigned char* lds, const Gemm g, const Epi& E) {
;     ...
;         for (int t = 0; t < nt; t += 2) {
;             const bool last = (t == nt - 2);
;             const char* a1 = cA + (size_t)(t + 1) * kstep;
;             const char* a2 = last ? nA : cA + (size_t)(t + 2) * kstep; const char* b2 = last ? nB : cB + (size_t)(t + 2) * kstep;
;             const char* a3 = a2 + kstep; const char* b3 = b2 + kstep;
;             PG8_LDB(B0, 0, 0); PG8_SCHED; PG8_LDA(At, 0, 0); PG8_STAGE(PG8_SA(1, 1), a1 + hstep, voffA);
;             PG8_WAIT_L(8); PG8_BAR; PG8_WAIT_L(0); PG8_MMA(0, 0, At, B0); PG8_BAR; PG8_SCHED;
;             PG8_LDB(B1, 0, 1); PG8_STAGE(PG8_SB(0, 0), b2, voffB);
;             PG8_BAR; PG8_WAIT_L(0); PG8_MMA(0, 1, At, B1); PG8_BAR;
;             PG8_LDA(At, 0, 1); PG8_STAGE(PG8_SA(0, 0), a2, voffA);
;             PG8_BAR; PG8_WAIT_L(0); PG8_MMA(1, 0, At, B0); PG8_BAR; PG8_SCHED;
;             PG8_STAGE(PG8_SB(0, 1), b2 + hstep, voffB);
;             PG8_WAIT_V(6); PG8_BAR; PG8_MMA(1, 1, At, B1); PG8_BAR;
;             PG8_LDB(B0, 1, 0); PG8_SCHED; PG8_LDA(At, 1, 0); PG8_STAGE(PG8_SA(0, 1), a2 + hstep, voffA);
;             PG8_WAIT_L(8); PG8_BAR; PG8_WAIT_L(0); PG8_MMA(0, 0, At, B0); PG8_BAR; PG8_SCHED;
.LBB0_672:
	s_add_u32 s28, s26, 0xfff80080
	s_addc_u32 s29, s27, -1
	s_add_i32 s34, 0, 0x10000
	v_add_u32_e32 v160, s34, v163
	ds_read_b128 v[128:131], v160
	ds_read_b128 v[132:135], v160 offset:1024
	ds_read_b128 v[156:159], v160 offset:2048
	ds_read_b128 v[166:169], v160 offset:3072
	s_cmp_eq_u32 s39, 28
	s_cselect_b32 s37, s1, s29
	s_cselect_b32 s36, s2, s28
	s_cselect_b32 s29, s3, s38
	s_cselect_b32 s28, s30, s31
	s_add_i32 m0, s96, 0xc000
	ds_read_b128 v[170:173], v164
	ds_read_b128 v[174:177], v164 offset:1024
	ds_read_b128 v[178:181], v164 offset:2048
	ds_read_b128 v[182:185], v164 offset:3072
	ds_read_b128 v[186:189], v164 offset:4096
	ds_read_b128 v[190:193], v164 offset:5120
	ds_read_b128 v[194:197], v164 offset:6144
	ds_read_b128 v[198:201], v164 offset:7168
	global_load_lds_dwordx4 v152, s[26:27]
	s_add_i32 m0, s96, 0xe000
	s_nop 0
	global_load_lds_dwordx4 v154, s[26:27]
	s_waitcnt lgkmcnt(8)
	s_barrier
	s_waitcnt lgkmcnt(0)
	s_setprio 1
	v_mfma_f32_16x16x32_bf16 v[124:127], v[128:131], v[170:173], v[124:127]
	v_mfma_f32_16x16x32_bf16 v[120:123], v[156:159], v[170:173], v[120:123]
	v_mfma_f32_16x16x32_bf16 v[108:111], v[128:131], v[178:181], v[108:111]
	v_mfma_f32_16x16x32_bf16 v[104:107], v[156:159], v[178:181], v[104:107]
	v_mfma_f32_16x16x32_bf16 v[92:95], v[128:131], v[186:189], v[92:95]
	v_mfma_f32_16x16x32_bf16 v[88:91], v[156:159], v[186:189], v[88:91]
	v_mfma_f32_16x16x32_bf16 v[76:79], v[128:131], v[194:197], v[76:79]
	v_mfma_f32_16x16x32_bf16 v[72:75], v[156:159], v[194:197], v[72:75]
	v_mfma_f32_16x16x32_bf16 v[124:127], v[132:135], v[174:177], v[124:127]
	v_mfma_f32_16x16x32_bf16 v[120:123], v[166:169], v[174:177], v[120:123]
	v_mfma_f32_16x16x32_bf16 v[108:111], v[132:135], v[182:185], v[108:111]
	v_mfma_f32_16x16x32_bf16 v[104:107], v[166:169], v[182:185], v[104:107]
	v_mfma_f32_16x16x32_bf16 v[92:95], v[132:135], v[190:193], v[92:95]
	v_mfma_f32_16x16x32_bf16 v[88:91], v[166:169], v[190:193], v[88:91]
	v_mfma_f32_16x16x32_bf16 v[76:79], v[132:135], v[198:201], v[76:79]
	v_mfma_f32_16x16x32_bf16 v[72:75], v[166:169], v[198:201], v[72:75]
	s_setprio 0
	s_barrier
	s_add_i32 s35, 0, 0x14000
	v_add_u32_e32 v160, s35, v163
	s_add_i32 s34, s34, s71
	ds_read_b128 v[202:205], v160
	ds_read_b128 v[238:241], v160 offset:1024
	ds_read_b128 v[242:245], v160 offset:2048
	ds_read_b128 v[246:249], v160 offset:3072
	s_mov_b32 m0, s34
	s_nop 0
	global_load_lds_dwordx4 v138, s[28:29]
	s_add_i32 m0, s34, 0x2000
	s_nop 0
	global_load_lds_dwordx4 v142, s[28:29]
	s_barrier
	s_waitcnt lgkmcnt(0)
	s_setprio 1
	v_mfma_f32_16x16x32_bf16 v[116:119], v[202:205], v[170:173], v[116:119]
	v_mfma_f32_16x16x32_bf16 v[112:115], v[242:245], v[170:173], v[112:115]
	v_mfma_f32_16x16x32_bf16 v[100:103], v[202:205], v[178:181], v[100:103]
	v_mfma_f32_16x16x32_bf16 v[96:99], v[242:245], v[178:181], v[96:99]
	v_mfma_f32_16x16x32_bf16 v[84:87], v[202:205], v[186:189], v[84:87]
	v_mfma_f32_16x16x32_bf16 v[80:83], v[242:245], v[186:189], v[80:83]
	v_mfma_f32_16x16x32_bf16 v[68:71], v[202:205], v[194:197], v[68:71]
	v_mfma_f32_16x16x32_bf16 v[64:67], v[242:245], v[194:197], v[64:67]
	v_mfma_f32_16x16x32_bf16 v[116:119], v[238:241], v[174:177], v[116:119]
	v_mfma_f32_16x16x32_bf16 v[112:115], v[246:249], v[174:177], v[112:115]
	v_mfma_f32_16x16x32_bf16 v[100:103], v[238:241], v[182:185], v[100:103]
	v_mfma_f32_16x16x32_bf16 v[96:99], v[246:249], v[182:185], v[96:99]
	v_mfma_f32_16x16x32_bf16 v[84:87], v[238:241], v[190:193], v[84:87]
	v_mfma_f32_16x16x32_bf16 v[80:83], v[246:249], v[190:193], v[80:83]
	v_mfma_f32_16x16x32_bf16 v[68:71], v[238:241], v[198:201], v[68:71]
	v_mfma_f32_16x16x32_bf16 v[64:67], v[246:249], v[198:201], v[64:67]
	s_setprio 0
	s_mov_b32 m0, s96
	s_barrier
	ds_read_b128 v[170:173], v164 offset:16384
	ds_read_b128 v[174:177], v164 offset:17408
	ds_read_b128 v[178:181], v164 offset:18432
	ds_read_b128 v[182:185], v164 offset:19456
	ds_read_b128 v[186:189], v164 offset:20480
	ds_read_b128 v[190:193], v164 offset:21504
	ds_read_b128 v[194:197], v164 offset:22528
	ds_read_b128 v[198:201], v164 offset:23552
	global_load_lds_dwordx4 v136, s[36:37]
	s_mov_b32 m0, s97
	s_nop 0
	global_load_lds_dwordx4 v140, s[36:37]
	s_barrier
	s_waitcnt lgkmcnt(0)
	s_setprio 1
	v_mfma_f32_16x16x32_bf16 v[60:63], v[128:131], v[170:173], v[60:63]
	v_mfma_f32_16x16x32_bf16 v[56:59], v[156:159], v[170:173], v[56:59]
	v_mfma_f32_16x16x32_bf16 v[44:47], v[128:131], v[178:181], v[44:47]
	v_mfma_f32_16x16x32_bf16 v[40:43], v[156:159], v[178:181], v[40:43]
	v_mfma_f32_16x16x32_bf16 v[28:31], v[128:131], v[186:189], v[28:31]
	v_mfma_f32_16x16x32_bf16 v[24:27], v[156:159], v[186:189], v[24:27]
	v_mfma_f32_16x16x32_bf16 v[12:15], v[128:131], v[194:197], v[12:15]
	v_mfma_f32_16x16x32_bf16 v[8:11], v[156:159], v[194:197], v[8:11]
	v_mfma_f32_16x16x32_bf16 v[60:63], v[132:135], v[174:177], v[60:63]
	v_mfma_f32_16x16x32_bf16 v[56:59], v[166:169], v[174:177], v[56:59]
	v_mfma_f32_16x16x32_bf16 v[44:47], v[132:135], v[182:185], v[44:47]
	v_mfma_f32_16x16x32_bf16 v[40:43], v[166:169], v[182:185], v[40:43]
	v_mfma_f32_16x16x32_bf16 v[28:31], v[132:135], v[190:193], v[28:31]
	v_mfma_f32_16x16x32_bf16 v[24:27], v[166:169], v[190:193], v[24:27]
	v_mfma_f32_16x16x32_bf16 v[12:15], v[132:135], v[198:201], v[12:15]
	v_mfma_f32_16x16x32_bf16 v[8:11], v[166:169], v[198:201], v[8:11]
	s_setprio 0
	s_barrier
	s_add_u32 s48, s28, 0x80000
	s_addc_u32 s49, s29, 0
	s_add_i32 s34, s35, s71
	s_mov_b32 m0, s34
	s_nop 0
	global_load_lds_dwordx4 v138, s[48:49]
	s_add_i32 m0, s34, 0x2000
	s_nop 0
	global_load_lds_dwordx4 v142, s[48:49]
	s_waitcnt vmcnt(6)
	s_barrier
; #define PG8_STAGE(bufoff, gbase, voff) do { _Pragma("unroll") for (int _i = 0; _i < 2; ++_i) \
;         __builtin_amdgcn_global_load_lds((const unsigned*)((const char*)(gbase) + (voff)[_i]), (LAS unsigned*)(lds + (bufoff) + ldsw + _i * 8192), 16, 0, 0); } while (0)
; #define PG8_LDA(dst, b, h) do { _Pragma("unroll") for (int m = 0; m < 4; ++m) _Pragma("unroll") for (int k = 0; k < 2; ++k) dst[m][k] = *(const LAS bf16x8*)(lds + PG8_SA(b, h) + aoff + m * 2048 + k * 1024); } while (0)
; #define PG8_LDB(dst, b, h) do { _Pragma("unroll") for (int n = 0; n < 2; ++n) _Pragma("unroll") for (int k = 0; k < 2; ++k) dst[n][k] = *(const LAS bf16x8*)(lds + PG8_SB(b, h) + boff + n * 2048 + k * 1024); } while (0)
; #define PG8_MMA(ai, bj, At, Bt) do { __builtin_amdgcn_s_setprio(1); _Pragma("unroll") for (int m = 0; m < 4; ++m) _Pragma("unroll") for (int n = 0; n < 2; ++n) _Pragma("unroll") for (int k = 0; k < 2; ++k) \
;         acc[ai][bj][m][n] = __builtin_amdgcn_mfma_f32_16x16x32_bf16(Bt[n][k], At[m][k], acc[ai][bj][m][n], 0, 0, 0); __builtin_amdgcn_s_setprio(0); } while (0)
; #define PG8_WAIT_V(n) asm volatile("s_waitcnt vmcnt(" #n ")" ::: "memory")
; #define PG8_WAIT_L(n) asm volatile("s_waitcnt lgkmcnt(" #n ")" ::: "memory")
; #define PG8_BAR __builtin_amdgcn_s_barrier()
; #define PG8_SCHED __builtin_amdgcn_sched_barrier(0)
; template <class Epi>
; __device__ __forceinline__ void gemm_phase(LAS unsigned char* lds, const Gemm g, const Epi& E) {
;     ...
;             PG8_WAIT_V(6); PG8_BAR; PG8_MMA(1, 1, At, B1); PG8_BAR;
;             PG8_LDB(B0, 1, 0); PG8_SCHED; PG8_LDA(At, 1, 0); PG8_STAGE(PG8_SA(0, 1), a2 + hstep, voffA);
;             PG8_WAIT_L(8); PG8_BAR; PG8_WAIT_L(0); PG8_MMA(0, 0, At, B0); PG8_BAR; PG8_SCHED;
;             PG8_LDB(B1, 1, 1); PG8_STAGE(PG8_SB(1, 0), b3, voffB);
;             PG8_BAR; PG8_WAIT_L(0); PG8_MMA(0, 1, At, B1); PG8_BAR;
;             PG8_LDA(At, 1, 1); PG8_STAGE(PG8_SA(1, 0), a3, voffA);
;             PG8_BAR; PG8_WAIT_L(0); PG8_MMA(1, 0, At, B0); PG8_BAR; PG8_SCHED;
	s_setprio 1
	v_mfma_f32_16x16x32_bf16 v[52:55], v[202:205], v[170:173], v[52:55]
	v_mfma_f32_16x16x32_bf16 v[48:51], v[242:245], v[170:173], v[48:51]
	v_mfma_f32_16x16x32_bf16 v[36:39], v[202:205], v[178:181], v[36:39]
	v_mfma_f32_16x16x32_bf16 v[32:35], v[242:245], v[178:181], v[32:35]
	v_mfma_f32_16x16x32_bf16 v[20:23], v[202:205], v[186:189], v[20:23]
	v_mfma_f32_16x16x32_bf16 v[16:19], v[242:245], v[186:189], v[16:19]
	v_mfma_f32_16x16x32_bf16 v[4:7], v[202:205], v[194:197], v[4:7]
	v_mfma_f32_16x16x32_bf16 v[0:3], v[242:245], v[194:197], v[0:3]
	v_mfma_f32_16x16x32_bf16 v[52:55], v[238:241], v[174:177], v[52:55]
	v_mfma_f32_16x16x32_bf16 v[48:51], v[246:249], v[174:177], v[48:51]
	v_mfma_f32_16x16x32_bf16 v[36:39], v[238:241], v[182:185], v[36:39]
	v_mfma_f32_16x16x32_bf16 v[32:35], v[246:249], v[182:185], v[32:35]
	v_mfma_f32_16x16x32_bf16 v[20:23], v[238:241], v[190:193], v[20:23]
	v_mfma_f32_16x16x32_bf16 v[16:19], v[246:249], v[190:193], v[16:19]
	v_mfma_f32_16x16x32_bf16 v[4:7], v[238:241], v[198:201], v[4:7]
	v_mfma_f32_16x16x32_bf16 v[0:3], v[246:249], v[198:201], v[0:3]
	s_setprio 0
	s_add_i32 s34, 0, 0x18000
	v_add_u32_e32 v165, s34, v163
	s_barrier
	ds_read_b128 v[128:131], v165
	ds_read_b128 v[132:135], v165 offset:1024
	ds_read_b128 v[156:159], v165 offset:2048
	ds_read_b128 v[166:169], v165 offset:3072
	s_add_u32 s36, s36, 0x80000
	s_addc_u32 s37, s37, 0
	s_mov_b32 m0, s70
	ds_read_b128 v[170:173], v164 offset:32768
	ds_read_b128 v[174:177], v164 offset:33792
	ds_read_b128 v[178:181], v164 offset:34816
	ds_read_b128 v[182:185], v164 offset:35840
	ds_read_b128 v[186:189], v164 offset:36864
	ds_read_b128 v[190:193], v164 offset:37888
	ds_read_b128 v[194:197], v164 offset:38912
	ds_read_b128 v[198:201], v164 offset:39936
	global_load_lds_dwordx4 v136, s[36:37]
	s_mov_b32 m0, s69
	s_nop 0
	global_load_lds_dwordx4 v140, s[36:37]
	s_waitcnt lgkmcnt(8)
	s_barrier
	s_waitcnt lgkmcnt(0)
	s_setprio 1
	v_mfma_f32_16x16x32_bf16 v[124:127], v[128:131], v[170:173], v[124:127]
	v_mfma_f32_16x16x32_bf16 v[120:123], v[156:159], v[170:173], v[120:123]
	v_mfma_f32_16x16x32_bf16 v[108:111], v[128:131], v[178:181], v[108:111]
	v_mfma_f32_16x16x32_bf16 v[104:107], v[156:159], v[178:181], v[104:107]
	v_mfma_f32_16x16x32_bf16 v[92:95], v[128:131], v[186:189], v[92:95]
	v_mfma_f32_16x16x32_bf16 v[88:91], v[156:159], v[186:189], v[88:91]
	v_mfma_f32_16x16x32_bf16 v[76:79], v[128:131], v[194:197], v[76:79]
	v_mfma_f32_16x16x32_bf16 v[72:75], v[156:159], v[194:197], v[72:75]
	v_mfma_f32_16x16x32_bf16 v[124:127], v[132:135], v[174:177], v[124:127]
	v_mfma_f32_16x16x32_bf16 v[120:123], v[166:169], v[174:177], v[120:123]
	v_mfma_f32_16x16x32_bf16 v[108:111], v[132:135], v[182:185], v[108:111]
	v_mfma_f32_16x16x32_bf16 v[104:107], v[166:169], v[182:185], v[104:107]
	v_mfma_f32_16x16x32_bf16 v[92:95], v[132:135], v[190:193], v[92:95]
	v_mfma_f32_16x16x32_bf16 v[88:91], v[166:169], v[190:193], v[88:91]
	v_mfma_f32_16x16x32_bf16 v[76:79], v[132:135], v[198:201], v[76:79]
	v_mfma_f32_16x16x32_bf16 v[72:75], v[166:169], v[198:201], v[72:75]
	s_setprio 0
	s_barrier
	s_add_i32 s35, 0, 0x1c000
	s_add_i32 s34, s34, s71
	v_add_u32_e32 v165, s35, v163
	s_mov_b32 m0, s34
	ds_read_b128 v[202:205], v165
	ds_read_b128 v[238:241], v165 offset:1024
	ds_read_b128 v[242:245], v165 offset:2048
	ds_read_b128 v[246:249], v165 offset:3072
	s_add_u32 s98, s28, 0x80
	s_addc_u32 s99, s29, 0
	global_load_lds_dwordx4 v138, s[98:99]
	s_add_i32 m0, s34, 0x2000
	s_add_u32 s100, s28, 0x80
	s_addc_u32 s101, s29, 0
	global_load_lds_dwordx4 v142, s[100:101]
	s_barrier
	s_waitcnt lgkmcnt(0)
	s_setprio 1
	v_mfma_f32_16x16x32_bf16 v[116:119], v[202:205], v[170:173], v[116:119]
	v_mfma_f32_16x16x32_bf16 v[112:115], v[242:245], v[170:173], v[112:115]
	v_mfma_f32_16x16x32_bf16 v[100:103], v[202:205], v[178:181], v[100:103]
	v_mfma_f32_16x16x32_bf16 v[96:99], v[242:245], v[178:181], v[96:99]
	v_mfma_f32_16x16x32_bf16 v[84:87], v[202:205], v[186:189], v[84:87]
	v_mfma_f32_16x16x32_bf16 v[80:83], v[242:245], v[186:189], v[80:83]
	v_mfma_f32_16x16x32_bf16 v[68:71], v[202:205], v[194:197], v[68:71]
	v_mfma_f32_16x16x32_bf16 v[64:67], v[242:245], v[194:197], v[64:67]
	v_mfma_f32_16x16x32_bf16 v[116:119], v[238:241], v[174:177], v[116:119]
	v_mfma_f32_16x16x32_bf16 v[112:115], v[246:249], v[174:177], v[112:115]
	v_mfma_f32_16x16x32_bf16 v[100:103], v[238:241], v[182:185], v[100:103]
	v_mfma_f32_16x16x32_bf16 v[96:99], v[246:249], v[182:185], v[96:99]
	v_mfma_f32_16x16x32_bf16 v[84:87], v[238:241], v[190:193], v[84:87]
	v_mfma_f32_16x16x32_bf16 v[80:83], v[246:249], v[190:193], v[80:83]
	v_mfma_f32_16x16x32_bf16 v[68:71], v[238:241], v[198:201], v[68:71]
	v_mfma_f32_16x16x32_bf16 v[64:67], v[246:249], v[198:201], v[64:67]
	s_setprio 0
	s_mov_b32 m0, s68
	s_barrier
; #define PG8_STAGE(bufoff, gbase, voff) do { _Pragma("unroll") for (int _i = 0; _i < 2; ++_i) \
;         __builtin_amdgcn_global_load_lds((const unsigned*)((const char*)(gbase) + (voff)[_i]), (LAS unsigned*)(lds + (bufoff) + ldsw + _i * 8192), 16, 0, 0); } while (0)
; #define PG8_LDA(dst, b, h) do { _Pragma("unroll") for (int m = 0; m < 4; ++m) _Pragma("unroll") for (int k = 0; k < 2; ++k) dst[m][k] = *(const LAS bf16x8*)(lds + PG8_SA(b, h) + aoff + m * 2048 + k * 1024); } while (0)
; #define PG8_LDB(dst, b, h) do { _Pragma("unroll") for (int n = 0; n < 2; ++n) _Pragma("unroll") for (int k = 0; k < 2; ++k) dst[n][k] = *(const LAS bf16x8*)(lds + PG8_SB(b, h) + boff + n * 2048 + k * 1024); } while (0)
; #define PG8_MMA(ai, bj, At, Bt) do { __builtin_amdgcn_s_setprio(1); _Pragma("unroll") for (int m = 0; m < 4; ++m) _Pragma("unroll") for (int n = 0; n < 2; ++n) _Pragma("unroll") for (int k = 0; k < 2; ++k) \
;         acc[ai][bj][m][n] = __builtin_amdgcn_mfma_f32_16x16x32_bf16(Bt[n][k], At[m][k], acc[ai][bj][m][n], 0, 0, 0); __builtin_amdgcn_s_setprio(0); } while (0)
; #define PG8_WAIT_V(n) asm volatile("s_waitcnt vmcnt(" #n ")" ::: "memory")
; #define PG8_WAIT_L(n) asm volatile("s_waitcnt lgkmcnt(" #n ")" ::: "memory")
; template <class Epi>
; __device__ __forceinline__ void gemm_phase(LAS unsigned char* lds, const Gemm g, const Epi& E) {
;     ...
;             PG8_WAIT_L(8); PG8_BAR; PG8_WAIT_L(0); PG8_MMA(0, 0, At, B0); PG8_BAR; PG8_SCHED;
;             PG8_LDB(B1, 1, 1); PG8_STAGE(PG8_SB(1, 0), b3, voffB);
;             PG8_BAR; PG8_WAIT_L(0); PG8_MMA(0, 1, At, B1); PG8_BAR;
;             PG8_LDA(At, 1, 1); PG8_STAGE(PG8_SA(1, 0), a3, voffA);
;             PG8_BAR; PG8_WAIT_L(0); PG8_MMA(1, 0, At, B0); PG8_BAR; PG8_SCHED;
;             PG8_STAGE(PG8_SB(1, 1), b3 + hstep, voffB);
;             PG8_WAIT_V(6); PG8_BAR; PG8_MMA(1, 1, At, B1); PG8_BAR;
;     __device__ __forceinline__ void operator()(const AccT& acc, const Unit& u, int wr, int wc, int fr, int fq) const {
;     ...
;                     const int row = u.pm * 256 + ai * 128 + wr * 64 + m * 16 + fr;
;                     const f32x4 v0 = acc[ai][0][m][0], v1 = acc[ai][0][m][1];
;                     if (g8 < 8) {
;                         const int i0 = 4 * g8;
;                         const f32x4 cs = *(const f32x4*)(COS + (size_t)row * 32 + i0), sn = *(const f32x4*)(SIN + (size_t)row * 32 + i0);
	ds_read_b128 v[170:173], v164 offset:49152
	ds_read_b128 v[174:177], v164 offset:50176
	ds_read_b128 v[178:181], v164 offset:51200
	ds_read_b128 v[182:185], v164 offset:52224
	ds_read_b128 v[186:189], v164 offset:53248
	ds_read_b128 v[190:193], v164 offset:54272
	ds_read_b128 v[194:197], v164 offset:55296
	ds_read_b128 v[198:201], v164 offset:56320
	s_add_u32 s98, s36, 0xfff80080
	s_addc_u32 s99, s37, -1
	global_load_lds_dwordx4 v136, s[98:99]
	s_mov_b32 m0, s83
	s_add_u32 s100, s36, 0xfff80080
	s_addc_u32 s101, s37, -1
	global_load_lds_dwordx4 v140, s[100:101]
	s_barrier
	s_waitcnt lgkmcnt(0)
	s_setprio 1
	v_mfma_f32_16x16x32_bf16 v[60:63], v[128:131], v[170:173], v[60:63]
	v_mfma_f32_16x16x32_bf16 v[56:59], v[156:159], v[170:173], v[56:59]
	v_mfma_f32_16x16x32_bf16 v[44:47], v[128:131], v[178:181], v[44:47]
	v_mfma_f32_16x16x32_bf16 v[40:43], v[156:159], v[178:181], v[40:43]
	v_mfma_f32_16x16x32_bf16 v[28:31], v[128:131], v[186:189], v[28:31]
	v_mfma_f32_16x16x32_bf16 v[24:27], v[156:159], v[186:189], v[24:27]
	v_mfma_f32_16x16x32_bf16 v[12:15], v[128:131], v[194:197], v[12:15]
	v_mfma_f32_16x16x32_bf16 v[8:11], v[156:159], v[194:197], v[8:11]
	v_mfma_f32_16x16x32_bf16 v[60:63], v[132:135], v[174:177], v[60:63]
	v_mfma_f32_16x16x32_bf16 v[56:59], v[166:169], v[174:177], v[56:59]
	v_mfma_f32_16x16x32_bf16 v[44:47], v[132:135], v[182:185], v[44:47]
	v_mfma_f32_16x16x32_bf16 v[40:43], v[166:169], v[182:185], v[40:43]
	v_mfma_f32_16x16x32_bf16 v[28:31], v[132:135], v[190:193], v[28:31]
	v_mfma_f32_16x16x32_bf16 v[24:27], v[166:169], v[190:193], v[24:27]
	v_mfma_f32_16x16x32_bf16 v[12:15], v[132:135], v[198:201], v[12:15]
	v_mfma_f32_16x16x32_bf16 v[8:11], v[166:169], v[198:201], v[8:11]
	s_setprio 0
	s_barrier
	s_add_u32 s28, s28, 0x80080
	s_addc_u32 s29, s29, 0
	s_add_i32 s34, s35, s71
	s_mov_b32 m0, s34
	s_nop 0
	global_load_lds_dwordx4 v138, s[28:29]
	s_add_i32 m0, s34, 0x2000
	s_nop 0
	global_load_lds_dwordx4 v142, s[28:29]
	s_waitcnt vmcnt(6)
	s_barrier
	s_setprio 1
	v_mfma_f32_16x16x32_bf16 v[52:55], v[202:205], v[170:173], v[52:55]
	v_mfma_f32_16x16x32_bf16 v[48:51], v[242:245], v[170:173], v[48:51]
	v_mfma_f32_16x16x32_bf16 v[36:39], v[202:205], v[178:181], v[36:39]
	v_mfma_f32_16x16x32_bf16 v[32:35], v[242:245], v[178:181], v[32:35]
	v_mfma_f32_16x16x32_bf16 v[20:23], v[202:205], v[186:189], v[20:23]
	v_mfma_f32_16x16x32_bf16 v[16:19], v[242:245], v[186:189], v[16:19]
	v_mfma_f32_16x16x32_bf16 v[4:7], v[202:205], v[194:197], v[4:7]
	v_mfma_f32_16x16x32_bf16 v[0:3], v[242:245], v[194:197], v[0:3]
	v_mfma_f32_16x16x32_bf16 v[52:55], v[238:241], v[174:177], v[52:55]
	v_mfma_f32_16x16x32_bf16 v[48:51], v[246:249], v[174:177], v[48:51]
	v_mfma_f32_16x16x32_bf16 v[36:39], v[238:241], v[182:185], v[36:39]
	v_mfma_f32_16x16x32_bf16 v[32:35], v[246:249], v[182:185], v[32:35]
	v_mfma_f32_16x16x32_bf16 v[20:23], v[238:241], v[190:193], v[20:23]
	v_mfma_f32_16x16x32_bf16 v[16:19], v[246:249], v[190:193], v[16:19]
	v_mfma_f32_16x16x32_bf16 v[4:7], v[238:241], v[198:201], v[4:7]
	v_mfma_f32_16x16x32_bf16 v[0:3], v[246:249], v[198:201], v[0:3]
	s_setprio 0
	s_add_i32 s39, s39, 2
	s_add_u32 s26, s26, 0x100
	s_addc_u32 s27, s27, 0
	s_add_u32 s31, s31, 0x100
	s_addc_u32 s38, s38, 0
	s_cmp_gt_u32 s39, 29
	s_barrier
	s_cbranch_scc0 .LBB0_672
	s_mov_b64 s[26:27], -1
	s_cmp_gt_i32 s64, 35
	v_lshl_add_u32 v156, s46, 8, v162
	s_movk_i32 s95, 0x1ff
	s_cbranch_scc0 .LBB0_723
	v_mov_b32_e32 v220, v156
	v_ashrrev_i32_e32 v221, 31, v156
	v_lshlrev_b64 v[220:221], 7, v[220:221]
	v_lshl_add_u64 v[200:201], v[146:147], 0, v[220:221]
	v_lshl_add_u64 v[202:203], v[148:149], 0, v[220:221]
	s_mov_b64 s[98:99], 0x1000
	v_lshl_add_u64 v[204:205], v[200:201], 0, s[98:99]
	v_lshl_add_u64 v[206:207], v[202:203], 0, s[98:99]
	global_load_dwordx4 v[168:171], v[200:201], off
	global_load_dwordx4 v[172:175], v[202:203], off
	global_load_dwordx4 v[176:179], v[200:201], off offset:2048
	global_load_dwordx4 v[180:183], v[202:203], off offset:2048
	global_load_dwordx4 v[184:187], v[204:205], off
	global_load_dwordx4 v[188:191], v[206:207], off
	global_load_dwordx4 v[192:195], v[204:205], off offset:2048
	global_load_dwordx4 v[196:199], v[206:207], off offset:2048
	s_mov_b64 s[98:99], 0x4000
	v_lshl_add_u64 v[200:201], v[200:201], 0, s[98:99]
	v_lshl_add_u64 v[202:203], v[202:203], 0, s[98:99]
	v_lshl_add_u64 v[204:205], v[204:205], 0, s[98:99]
	v_lshl_add_u64 v[206:207], v[206:207], 0, s[98:99]
	s_and_b64 vcc, exec, s[52:53]
	s_cbranch_vccz .LBB0_678
	s_and_saveexec_b64 s[26:27], s[54:55]
	s_cbranch_execz .LBB0_677
	v_ashrrev_i32_e32 v157, 31, v156
	v_lshlrev_b64 v[128:129], 6, v[156:157]
	v_lshl_add_u64 v[128:129], v[144:145], 0, v[128:129]
	global_store_dwordx4 v[128:129], v[124:127], off offset:-256
	global_store_dwordx4 v[128:129], v[120:123], off offset:-240

; __device__ __forceinline__ u32x2 pack4u(f32x4 a) { u32x2 w = {cvt_pk_bf16(a[0], a[1]), cvt_pk_bf16(a[2], a[3])}; return w; }
;     __device__ __forceinline__ void operator()(const AccT& acc, const Unit& u, int wr, int wc, int fr, int fq) const {
;     ...
;                     if (g8 < 8) {
;                         const int i0 = 4 * g8;
;                         const f32x4 cs = *(const f32x4*)(COS + (size_t)row * 32 + i0), sn = *(const f32x4*)(SIN + (size_t)row * 32 + i0);
;                         const f32x4 o1 = v0 * cs - v1 * sn, o2 = v1 * cs + v0 * sn;
;                         const u32x2 w1 = pack4u(o1), w2 = pack4u(o2);
;                         const int b = row / SEQ, t = row % SEQ;
;                         bf16_t* kp = Kb + ((size_t)(b * NH) * SEQ + t) * DQK + 128 + i0;
; #pragma unroll
;                         for (int h = 0; h < NH; ++h) { *(u32x2*)(kp + (size_t)h * SEQ * DQK) = w1; *(u32x2*)(kp + (size_t)h * SEQ * DQK + 32) = w2; }
.LBB0_678:
	s_andn2_b64 vcc, exec, s[26:27]
	s_cbranch_vccnz .LBB0_680
	v_ashrrev_i32_e32 v157, 31, v156
	v_lshlrev_b64 v[132:133], 7, v[156:157]
	v_lshl_add_u64 v[128:129], v[146:147], 0, v[132:133]
	v_lshl_add_u64 v[132:133], v[148:149], 0, v[132:133]
	s_waitcnt vmcnt(6)
	v_mov_b32_e32 v128, v168
	v_mov_b32_e32 v129, v169
	v_mov_b32_e32 v130, v170
	v_mov_b32_e32 v131, v171
	s_nop 0
	v_mov_b32_e32 v132, v172
	v_mov_b32_e32 v133, v173
	v_mov_b32_e32 v134, v174
	v_mov_b32_e32 v135, v175
	global_load_dwordx4 v[168:171], v[200:201], off
	global_load_dwordx4 v[172:175], v[202:203], off
	s_nop 0
	v_pk_mul_f32 v[158:159], v[122:123], v[134:135]
	v_pk_mul_f32 v[160:161], v[120:121], v[132:133]
	v_pk_mul_f32 v[134:135], v[126:127], v[134:135]
	v_pk_mul_f32 v[132:133], v[124:125], v[132:133]
	v_pk_fma_f32 v[158:159], v[126:127], v[130:131], v[158:159] neg_lo:[0,0,1] neg_hi:[0,0,1]
	v_pk_fma_f32 v[134:135], v[122:123], v[130:131], v[134:135]
	v_pk_fma_f32 v[130:131], v[120:121], v[128:129], v[132:133]
	v_lshrrev_b32_e32 v132, 21, v157
	v_add_u32_e32 v132, v156, v132
	v_ashrrev_i32_e32 v133, 11, v132
	v_cvt_pk_bf16_f32 v130, v130, v131
	v_cvt_pk_bf16_f32 v131, v134, v135
	v_mul_i32_i24_e32 v132, 0x800, v133
	v_lshlrev_b32_e32 v134, 3, v133
	v_sub_u32_e32 v132, v156, v132
	v_ashrrev_i32_e32 v135, 31, v134
	v_lshlrev_b64 v[134:135], 11, v[134:135]
	v_ashrrev_i32_e32 v133, 31, v132
	v_lshl_add_u64 v[132:133], v[134:135], 0, v[132:133]
	v_mad_u64_u32 v[134:135], s[2:3], v132, s33, v[150:151]
	v_pk_fma_f32 v[160:161], v[124:125], v[128:129], v[160:161] neg_lo:[0,0,1] neg_hi:[0,0,1]
	v_mad_i32_i24 v135, v133, s33, v135
	v_add_co_u32_e32 v132, vcc, s76, v134
	v_cvt_pk_bf16_f32 v128, v160, v161
	v_cvt_pk_bf16_f32 v129, v158, v159
	v_addc_co_u32_e32 v133, vcc, 0, v135, vcc
	global_store_dwordx2 v[134:135], v[128:129], off offset:256
	global_store_dwordx2 v[134:135], v[130:131], off offset:320
	global_store_dwordx2 v[132:133], v[128:129], off offset:256
	global_store_dwordx2 v[132:133], v[130:131], off offset:320
	v_add_co_u32_e32 v132, vcc, s78, v134
	s_nop 1
	v_addc_co_u32_e32 v133, vcc, 0, v135, vcc
	global_store_dwordx2 v[132:133], v[128:129], off offset:256
	global_store_dwordx2 v[132:133], v[130:131], off offset:320
	v_add_co_u32_e32 v132, vcc, s82, v134
	s_nop 1
	v_addc_co_u32_e32 v133, vcc, 0, v135, vcc
	global_store_dwordx2 v[132:133], v[128:129], off offset:256
	global_store_dwordx2 v[132:133], v[130:131], off offset:320
	v_add_co_u32_e32 v132, vcc, s90, v134
	s_nop 1
	v_addc_co_u32_e32 v133, vcc, 0, v135, vcc
	global_store_dwordx2 v[132:133], v[128:129], off offset:256
	global_store_dwordx2 v[132:133], v[130:131], off offset:320
	v_add_co_u32_e32 v132, vcc, 0x3c0000, v134
	s_nop 1
	v_addc_co_u32_e32 v133, vcc, 0, v135, vcc
	global_store_dwordx2 v[132:133], v[128:129], off offset:256
	global_store_dwordx2 v[132:133], v[130:131], off offset:320
	v_add_co_u32_e32 v132, vcc, 0x480000, v134
	s_nop 1
	v_addc_co_u32_e32 v133, vcc, 0, v135, vcc
	global_store_dwordx2 v[132:133], v[128:129], off offset:256
	global_store_dwordx2 v[132:133], v[130:131], off offset:320
	v_add_co_u32_e32 v132, vcc, 0x540000, v134
	s_nop 1
	v_addc_co_u32_e32 v133, vcc, 0, v135, vcc
	global_store_dwordx2 v[132:133], v[128:129], off offset:256
	global_store_dwordx2 v[132:133], v[130:131], off offset:320

; __device__ __forceinline__ u32x2 pack4u(f32x4 a) { u32x2 w = {cvt_pk_bf16(a[0], a[1]), cvt_pk_bf16(a[2], a[3])}; return w; }
;     __device__ __forceinline__ void operator()(const AccT& acc, const Unit& u, int wr, int wc, int fr, int fq) const {
;     ...
;                     if (g8 < 8) {
;                         const int i0 = 4 * g8;
;                         const f32x4 cs = *(const f32x4*)(COS + (size_t)row * 32 + i0), sn = *(const f32x4*)(SIN + (size_t)row * 32 + i0);
;                         const f32x4 o1 = v0 * cs - v1 * sn, o2 = v1 * cs + v0 * sn;
;                         const u32x2 w1 = pack4u(o1), w2 = pack4u(o2);
;                         const int b = row / SEQ, t = row % SEQ;
;                         bf16_t* kp = Kb + ((size_t)(b * NH) * SEQ + t) * DQK + 128 + i0;
; #pragma unroll
;                         for (int h = 0; h < NH; ++h) { *(u32x2*)(kp + (size_t)h * SEQ * DQK) = w1; *(u32x2*)(kp + (size_t)h * SEQ * DQK + 32) = w2; }
.LBB0_709:
	v_ashrrev_i32_e32 v133, 31, v132
	v_lshlrev_b64 v[134:135], 7, v[132:133]
	v_lshl_add_u64 v[128:129], v[146:147], 0, v[134:135]
	v_lshl_add_u64 v[134:135], v[148:149], 0, v[134:135]
	s_waitcnt vmcnt(6)
	v_mov_b32_e32 v128, v176
	v_mov_b32_e32 v129, v177
	v_mov_b32_e32 v130, v178
	v_mov_b32_e32 v131, v179
	v_lshrrev_b32_e32 v133, 21, v133
	v_mov_b32_e32 v158, v180
	v_mov_b32_e32 v159, v181
	v_mov_b32_e32 v160, v182
	v_mov_b32_e32 v161, v183
	global_load_dwordx4 v[176:179], v[200:201], off offset:2048
	global_load_dwordx4 v[180:183], v[202:203], off offset:2048
	v_add_u32_e32 v133, v132, v133
	v_ashrrev_i32_e32 v133, 11, v133
	s_nop 0
	v_pk_mul_f32 v[134:135], v[106:107], v[160:161]
	v_pk_mul_f32 v[166:167], v[104:105], v[158:159]
	v_pk_fma_f32 v[134:135], v[110:111], v[130:131], v[134:135] neg_lo:[0,0,1] neg_hi:[0,0,1]
	v_pk_mul_f32 v[160:161], v[110:111], v[160:161]
	v_pk_mul_f32 v[158:159], v[108:109], v[158:159]
	v_pk_fma_f32 v[166:167], v[108:109], v[128:129], v[166:167] neg_lo:[0,0,1] neg_hi:[0,0,1]
	v_pk_fma_f32 v[160:161], v[106:107], v[130:131], v[160:161]
	v_pk_fma_f32 v[130:131], v[104:105], v[128:129], v[158:159]
	v_cvt_pk_bf16_f32 v129, v134, v135
	v_mul_i32_i24_e32 v134, 0x800, v133
	v_sub_u32_e32 v132, v132, v134
	v_lshlrev_b32_e32 v134, 3, v133
	v_ashrrev_i32_e32 v135, 31, v134
	v_lshlrev_b64 v[134:135], 11, v[134:135]
	v_ashrrev_i32_e32 v133, 31, v132
	v_lshl_add_u64 v[132:133], v[134:135], 0, v[132:133]
	v_mad_u64_u32 v[134:135], s[2:3], v132, s33, v[150:151]
	v_mad_i32_i24 v135, v133, s33, v135
	v_add_co_u32_e32 v132, vcc, s76, v134
	v_cvt_pk_bf16_f32 v128, v166, v167
	s_nop 0
	v_addc_co_u32_e32 v133, vcc, 0, v135, vcc
	v_cvt_pk_bf16_f32 v130, v130, v131
	v_cvt_pk_bf16_f32 v131, v160, v161
	global_store_dwordx2 v[134:135], v[128:129], off offset:256
	global_store_dwordx2 v[134:135], v[130:131], off offset:320
	global_store_dwordx2 v[132:133], v[128:129], off offset:256
	global_store_dwordx2 v[132:133], v[130:131], off offset:320
	v_add_co_u32_e32 v132, vcc, s78, v134
	s_nop 1
	v_addc_co_u32_e32 v133, vcc, 0, v135, vcc
	global_store_dwordx2 v[132:133], v[128:129], off offset:256
	global_store_dwordx2 v[132:133], v[130:131], off offset:320
	v_add_co_u32_e32 v132, vcc, s82, v134
	s_nop 1
	v_addc_co_u32_e32 v133, vcc, 0, v135, vcc
	global_store_dwordx2 v[132:133], v[128:129], off offset:256
	global_store_dwordx2 v[132:133], v[130:131], off offset:320
	v_add_co_u32_e32 v132, vcc, s90, v134
	s_nop 1
	v_addc_co_u32_e32 v133, vcc, 0, v135, vcc
	global_store_dwordx2 v[132:133], v[128:129], off offset:256
	global_store_dwordx2 v[132:133], v[130:131], off offset:320
	v_add_co_u32_e32 v132, vcc, 0x3c0000, v134
	s_nop 1
	v_addc_co_u32_e32 v133, vcc, 0, v135, vcc
	global_store_dwordx2 v[132:133], v[128:129], off offset:256
	global_store_dwordx2 v[132:133], v[130:131], off offset:320
	v_add_co_u32_e32 v132, vcc, 0x480000, v134
	s_nop 1
	v_addc_co_u32_e32 v133, vcc, 0, v135, vcc
	global_store_dwordx2 v[132:133], v[128:129], off offset:256
	global_store_dwordx2 v[132:133], v[130:131], off offset:320
	v_add_co_u32_e32 v132, vcc, 0x540000, v134
	s_nop 1
	v_addc_co_u32_e32 v133, vcc, 0, v135, vcc
	global_store_dwordx2 v[132:133], v[128:129], off offset:256
	global_store_dwordx2 v[132:133], v[130:131], off offset:320
	v_or_b32_e32 v132, 32, v156
	s_and_b64 vcc, exec, s[46:47]
	s_mov_b64 s[26:27], -1
	s_cbranch_vccz .LBB0_685

; __device__ __forceinline__ u32x2 pack4u(f32x4 a) { u32x2 w = {cvt_pk_bf16(a[0], a[1]), cvt_pk_bf16(a[2], a[3])}; return w; }
;     __device__ __forceinline__ void operator()(const AccT& acc, const Unit& u, int wr, int wc, int fr, int fq) const {
;     ...
;                     if (g8 < 8) {
;                         const int i0 = 4 * g8;
;                         const f32x4 cs = *(const f32x4*)(COS + (size_t)row * 32 + i0), sn = *(const f32x4*)(SIN + (size_t)row * 32 + i0);
;                         const f32x4 o1 = v0 * cs - v1 * sn, o2 = v1 * cs + v0 * sn;
;                         const u32x2 w1 = pack4u(o1), w2 = pack4u(o2);
;                         const int b = row / SEQ, t = row % SEQ;
;                         bf16_t* kp = Kb + ((size_t)(b * NH) * SEQ + t) * DQK + 128 + i0;
; #pragma unroll
;                         for (int h = 0; h < NH; ++h) { *(u32x2*)(kp + (size_t)h * SEQ * DQK) = w1; *(u32x2*)(kp + (size_t)h * SEQ * DQK + 32) = w2; }
.LBB0_711:
	v_ashrrev_i32_e32 v133, 31, v132
	v_lshlrev_b64 v[134:135], 7, v[132:133]
	v_lshl_add_u64 v[128:129], v[146:147], 0, v[134:135]
	v_lshl_add_u64 v[134:135], v[148:149], 0, v[134:135]
	s_waitcnt vmcnt(6)
	v_mov_b32_e32 v128, v184
	v_mov_b32_e32 v129, v185
	v_mov_b32_e32 v130, v186
	v_mov_b32_e32 v131, v187
	v_lshrrev_b32_e32 v133, 21, v133
	v_mov_b32_e32 v158, v188
	v_mov_b32_e32 v159, v189
	v_mov_b32_e32 v160, v190
	v_mov_b32_e32 v161, v191
	global_load_dwordx4 v[184:187], v[204:205], off
	global_load_dwordx4 v[188:191], v[206:207], off
	v_add_u32_e32 v133, v132, v133
	v_ashrrev_i32_e32 v133, 11, v133
	s_nop 0
	v_pk_mul_f32 v[134:135], v[90:91], v[160:161]
	v_pk_mul_f32 v[166:167], v[88:89], v[158:159]
	v_pk_fma_f32 v[134:135], v[94:95], v[130:131], v[134:135] neg_lo:[0,0,1] neg_hi:[0,0,1]
	v_pk_mul_f32 v[160:161], v[94:95], v[160:161]
	v_pk_mul_f32 v[158:159], v[92:93], v[158:159]
	v_pk_fma_f32 v[166:167], v[92:93], v[128:129], v[166:167] neg_lo:[0,0,1] neg_hi:[0,0,1]
	v_pk_fma_f32 v[160:161], v[90:91], v[130:131], v[160:161]
	v_pk_fma_f32 v[130:131], v[88:89], v[128:129], v[158:159]
	v_cvt_pk_bf16_f32 v129, v134, v135
	v_mul_i32_i24_e32 v134, 0x800, v133
	v_sub_u32_e32 v132, v132, v134
	v_lshlrev_b32_e32 v134, 3, v133
	v_ashrrev_i32_e32 v135, 31, v134
	v_lshlrev_b64 v[134:135], 11, v[134:135]
	v_ashrrev_i32_e32 v133, 31, v132
	v_lshl_add_u64 v[132:133], v[134:135], 0, v[132:133]
	v_mad_u64_u32 v[134:135], s[2:3], v132, s33, v[150:151]
	v_mad_i32_i24 v135, v133, s33, v135
	v_add_co_u32_e32 v132, vcc, s76, v134
	v_cvt_pk_bf16_f32 v128, v166, v167
	s_nop 0
	v_addc_co_u32_e32 v133, vcc, 0, v135, vcc
	v_cvt_pk_bf16_f32 v130, v130, v131
	v_cvt_pk_bf16_f32 v131, v160, v161
	global_store_dwordx2 v[134:135], v[128:129], off offset:256
	global_store_dwordx2 v[134:135], v[130:131], off offset:320
	global_store_dwordx2 v[132:133], v[128:129], off offset:256
	global_store_dwordx2 v[132:133], v[130:131], off offset:320
	v_add_co_u32_e32 v132, vcc, s78, v134
	s_nop 1
	v_addc_co_u32_e32 v133, vcc, 0, v135, vcc
	global_store_dwordx2 v[132:133], v[128:129], off offset:256
	global_store_dwordx2 v[132:133], v[130:131], off offset:320
	v_add_co_u32_e32 v132, vcc, s82, v134
	s_nop 1
	v_addc_co_u32_e32 v133, vcc, 0, v135, vcc
	global_store_dwordx2 v[132:133], v[128:129], off offset:256
	global_store_dwordx2 v[132:133], v[130:131], off offset:320
	v_add_co_u32_e32 v132, vcc, s90, v134
	s_nop 1
	v_addc_co_u32_e32 v133, vcc, 0, v135, vcc
	global_store_dwordx2 v[132:133], v[128:129], off offset:256
	global_store_dwordx2 v[132:133], v[130:131], off offset:320
	v_add_co_u32_e32 v132, vcc, 0x3c0000, v134
	s_nop 1
	v_addc_co_u32_e32 v133, vcc, 0, v135, vcc
	global_store_dwordx2 v[132:133], v[128:129], off offset:256
	global_store_dwordx2 v[132:133], v[130:131], off offset:320
	v_add_co_u32_e32 v132, vcc, 0x480000, v134
	s_nop 1
	v_addc_co_u32_e32 v133, vcc, 0, v135, vcc
	global_store_dwordx2 v[132:133], v[128:129], off offset:256
	global_store_dwordx2 v[132:133], v[130:131], off offset:320
	v_add_co_u32_e32 v132, vcc, 0x540000, v134
	s_nop 1
	v_addc_co_u32_e32 v133, vcc, 0, v135, vcc
	global_store_dwordx2 v[132:133], v[128:129], off offset:256
	global_store_dwordx2 v[132:133], v[130:131], off offset:320
	v_or_b32_e32 v132, 48, v156
	s_and_b64 vcc, exec, s[46:47]
	s_mov_b64 s[26:27], -1
	s_cbranch_vccz .LBB0_689

; __device__ __forceinline__ u32x2 pack4u(f32x4 a) { u32x2 w = {cvt_pk_bf16(a[0], a[1]), cvt_pk_bf16(a[2], a[3])}; return w; }
;     __device__ __forceinline__ void operator()(const AccT& acc, const Unit& u, int wr, int wc, int fr, int fq) const {
;     ...
;                     if (g8 < 8) {
;                         const int i0 = 4 * g8;
;                         const f32x4 cs = *(const f32x4*)(COS + (size_t)row * 32 + i0), sn = *(const f32x4*)(SIN + (size_t)row * 32 + i0);
;                         const f32x4 o1 = v0 * cs - v1 * sn, o2 = v1 * cs + v0 * sn;
;                         const u32x2 w1 = pack4u(o1), w2 = pack4u(o2);
;                         const int b = row / SEQ, t = row % SEQ;
;                         bf16_t* kp = Kb + ((size_t)(b * NH) * SEQ + t) * DQK + 128 + i0;
; #pragma unroll
;                         for (int h = 0; h < NH; ++h) { *(u32x2*)(kp + (size_t)h * SEQ * DQK) = w1; *(u32x2*)(kp + (size_t)h * SEQ * DQK + 32) = w2; }
.LBB0_713:
	v_ashrrev_i32_e32 v133, 31, v132
	v_lshlrev_b64 v[134:135], 7, v[132:133]
	v_lshl_add_u64 v[128:129], v[146:147], 0, v[134:135]
	v_lshl_add_u64 v[134:135], v[148:149], 0, v[134:135]
	s_waitcnt vmcnt(6)
	v_mov_b32_e32 v128, v192
	v_mov_b32_e32 v129, v193
	v_mov_b32_e32 v130, v194
	v_mov_b32_e32 v131, v195
	v_lshrrev_b32_e32 v133, 21, v133
	v_mov_b32_e32 v158, v196
	v_mov_b32_e32 v159, v197
	v_mov_b32_e32 v160, v198
	v_mov_b32_e32 v161, v199
	global_load_dwordx4 v[192:195], v[204:205], off offset:2048
	global_load_dwordx4 v[196:199], v[206:207], off offset:2048
	v_add_u32_e32 v133, v132, v133
	v_ashrrev_i32_e32 v133, 11, v133
	s_nop 0
	v_pk_mul_f32 v[134:135], v[74:75], v[160:161]
	v_pk_mul_f32 v[166:167], v[72:73], v[158:159]
	v_pk_fma_f32 v[134:135], v[78:79], v[130:131], v[134:135] neg_lo:[0,0,1] neg_hi:[0,0,1]
	v_pk_mul_f32 v[160:161], v[78:79], v[160:161]
	v_pk_mul_f32 v[158:159], v[76:77], v[158:159]
	v_pk_fma_f32 v[166:167], v[76:77], v[128:129], v[166:167] neg_lo:[0,0,1] neg_hi:[0,0,1]
	v_pk_fma_f32 v[160:161], v[74:75], v[130:131], v[160:161]
	v_pk_fma_f32 v[130:131], v[72:73], v[128:129], v[158:159]
	v_cvt_pk_bf16_f32 v129, v134, v135
	v_mul_i32_i24_e32 v134, 0x800, v133
	v_sub_u32_e32 v132, v132, v134
	v_lshlrev_b32_e32 v134, 3, v133
	v_ashrrev_i32_e32 v135, 31, v134
	v_lshlrev_b64 v[134:135], 11, v[134:135]
	v_ashrrev_i32_e32 v133, 31, v132
	v_lshl_add_u64 v[132:133], v[134:135], 0, v[132:133]
	v_mad_u64_u32 v[134:135], s[2:3], v132, s33, v[150:151]
	v_mad_i32_i24 v135, v133, s33, v135
	v_add_co_u32_e32 v132, vcc, s76, v134
	v_cvt_pk_bf16_f32 v128, v166, v167
	s_nop 0
	v_addc_co_u32_e32 v133, vcc, 0, v135, vcc
	v_cvt_pk_bf16_f32 v130, v130, v131
	v_cvt_pk_bf16_f32 v131, v160, v161
	global_store_dwordx2 v[134:135], v[128:129], off offset:256
	global_store_dwordx2 v[134:135], v[130:131], off offset:320
	global_store_dwordx2 v[132:133], v[128:129], off offset:256
	global_store_dwordx2 v[132:133], v[130:131], off offset:320
	v_add_co_u32_e32 v132, vcc, s78, v134
	s_nop 1
	v_addc_co_u32_e32 v133, vcc, 0, v135, vcc
	global_store_dwordx2 v[132:133], v[128:129], off offset:256
	global_store_dwordx2 v[132:133], v[130:131], off offset:320
	v_add_co_u32_e32 v132, vcc, s82, v134
	s_nop 1
	v_addc_co_u32_e32 v133, vcc, 0, v135, vcc
	global_store_dwordx2 v[132:133], v[128:129], off offset:256
	global_store_dwordx2 v[132:133], v[130:131], off offset:320
	v_add_co_u32_e32 v132, vcc, s90, v134
	s_nop 1
	v_addc_co_u32_e32 v133, vcc, 0, v135, vcc
	global_store_dwordx2 v[132:133], v[128:129], off offset:256
	global_store_dwordx2 v[132:133], v[130:131], off offset:320
	v_add_co_u32_e32 v132, vcc, 0x3c0000, v134
	s_nop 1
	v_addc_co_u32_e32 v133, vcc, 0, v135, vcc
	global_store_dwordx2 v[132:133], v[128:129], off offset:256
	global_store_dwordx2 v[132:133], v[130:131], off offset:320
	v_add_co_u32_e32 v132, vcc, 0x480000, v134
	s_nop 1
	v_addc_co_u32_e32 v133, vcc, 0, v135, vcc
	global_store_dwordx2 v[132:133], v[128:129], off offset:256
	global_store_dwordx2 v[132:133], v[130:131], off offset:320
	v_add_co_u32_e32 v132, vcc, 0x540000, v134
	s_nop 1
	v_addc_co_u32_e32 v133, vcc, 0, v135, vcc
	global_store_dwordx2 v[132:133], v[128:129], off offset:256
	global_store_dwordx2 v[132:133], v[130:131], off offset:320
	v_add_u32_e32 v132, 0x80, v156
	s_and_b64 vcc, exec, s[46:47]
	s_mov_b64 s[26:27], -1
	s_cbranch_vccz .LBB0_693

; __device__ __forceinline__ u32x2 pack4u(f32x4 a) { u32x2 w = {cvt_pk_bf16(a[0], a[1]), cvt_pk_bf16(a[2], a[3])}; return w; }
;     __device__ __forceinline__ void operator()(const AccT& acc, const Unit& u, int wr, int wc, int fr, int fq) const {
;     ...
;                     if (g8 < 8) {
;                         const int i0 = 4 * g8;
;                         const f32x4 cs = *(const f32x4*)(COS + (size_t)row * 32 + i0), sn = *(const f32x4*)(SIN + (size_t)row * 32 + i0);
;                         const f32x4 o1 = v0 * cs - v1 * sn, o2 = v1 * cs + v0 * sn;
;                         const u32x2 w1 = pack4u(o1), w2 = pack4u(o2);
;                         const int b = row / SEQ, t = row % SEQ;
;                         bf16_t* kp = Kb + ((size_t)(b * NH) * SEQ + t) * DQK + 128 + i0;
; #pragma unroll
;                         for (int h = 0; h < NH; ++h) { *(u32x2*)(kp + (size_t)h * SEQ * DQK) = w1; *(u32x2*)(kp + (size_t)h * SEQ * DQK + 32) = w2; }
.LBB0_715:
	v_ashrrev_i32_e32 v133, 31, v132
	v_lshlrev_b64 v[134:135], 7, v[132:133]
	v_lshl_add_u64 v[128:129], v[146:147], 0, v[134:135]
	v_lshl_add_u64 v[134:135], v[148:149], 0, v[134:135]
	s_waitcnt vmcnt(6)
	v_mov_b32_e32 v128, v168
	v_mov_b32_e32 v129, v169
	v_mov_b32_e32 v130, v170
	v_mov_b32_e32 v131, v171
	v_lshrrev_b32_e32 v133, 21, v133
	v_mov_b32_e32 v158, v172
	v_mov_b32_e32 v159, v173
	v_mov_b32_e32 v160, v174
	v_mov_b32_e32 v161, v175
	v_add_u32_e32 v133, v132, v133
	v_ashrrev_i32_e32 v133, 11, v133
	s_nop 0
	v_pk_mul_f32 v[134:135], v[58:59], v[160:161]
	v_pk_mul_f32 v[166:167], v[56:57], v[158:159]
	v_pk_fma_f32 v[134:135], v[62:63], v[130:131], v[134:135] neg_lo:[0,0,1] neg_hi:[0,0,1]
	v_pk_mul_f32 v[160:161], v[62:63], v[160:161]
	v_pk_mul_f32 v[158:159], v[60:61], v[158:159]
	v_pk_fma_f32 v[166:167], v[60:61], v[128:129], v[166:167] neg_lo:[0,0,1] neg_hi:[0,0,1]
	v_pk_fma_f32 v[160:161], v[58:59], v[130:131], v[160:161]
	v_pk_fma_f32 v[130:131], v[56:57], v[128:129], v[158:159]
	v_cvt_pk_bf16_f32 v129, v134, v135
	v_mul_i32_i24_e32 v134, 0x800, v133
	v_sub_u32_e32 v132, v132, v134
	v_lshlrev_b32_e32 v134, 3, v133
	v_ashrrev_i32_e32 v135, 31, v134
	v_lshlrev_b64 v[134:135], 11, v[134:135]
	v_ashrrev_i32_e32 v133, 31, v132
	v_lshl_add_u64 v[132:133], v[134:135], 0, v[132:133]
	v_mad_u64_u32 v[134:135], s[2:3], v132, s33, v[150:151]
	v_mad_i32_i24 v135, v133, s33, v135
	v_add_co_u32_e32 v132, vcc, s76, v134
	v_cvt_pk_bf16_f32 v128, v166, v167
	s_nop 0
	v_addc_co_u32_e32 v133, vcc, 0, v135, vcc
	v_cvt_pk_bf16_f32 v130, v130, v131
	v_cvt_pk_bf16_f32 v131, v160, v161
	global_store_dwordx2 v[134:135], v[128:129], off offset:256
	global_store_dwordx2 v[134:135], v[130:131], off offset:320
	global_store_dwordx2 v[132:133], v[128:129], off offset:256
	global_store_dwordx2 v[132:133], v[130:131], off offset:320
	v_add_co_u32_e32 v132, vcc, s78, v134
	s_nop 1
	v_addc_co_u32_e32 v133, vcc, 0, v135, vcc
	global_store_dwordx2 v[132:133], v[128:129], off offset:256
	global_store_dwordx2 v[132:133], v[130:131], off offset:320
	v_add_co_u32_e32 v132, vcc, s82, v134
	s_nop 1
	v_addc_co_u32_e32 v133, vcc, 0, v135, vcc
	global_store_dwordx2 v[132:133], v[128:129], off offset:256
	global_store_dwordx2 v[132:133], v[130:131], off offset:320
	v_add_co_u32_e32 v132, vcc, s90, v134
	s_nop 1
	v_addc_co_u32_e32 v133, vcc, 0, v135, vcc
	global_store_dwordx2 v[132:133], v[128:129], off offset:256
	global_store_dwordx2 v[132:133], v[130:131], off offset:320
	v_add_co_u32_e32 v132, vcc, 0x3c0000, v134
	s_nop 1
	v_addc_co_u32_e32 v133, vcc, 0, v135, vcc
	global_store_dwordx2 v[132:133], v[128:129], off offset:256
	global_store_dwordx2 v[132:133], v[130:131], off offset:320
	v_add_co_u32_e32 v132, vcc, 0x480000, v134
	s_nop 1
	v_addc_co_u32_e32 v133, vcc, 0, v135, vcc
	global_store_dwordx2 v[132:133], v[128:129], off offset:256
	global_store_dwordx2 v[132:133], v[130:131], off offset:320
	v_add_co_u32_e32 v132, vcc, 0x540000, v134
	s_nop 1
	v_addc_co_u32_e32 v133, vcc, 0, v135, vcc
	global_store_dwordx2 v[132:133], v[128:129], off offset:256
	global_store_dwordx2 v[132:133], v[130:131], off offset:320
	v_add_u32_e32 v132, 0x90, v156
	s_and_b64 vcc, exec, s[46:47]
	s_mov_b64 s[26:27], -1
	s_cbranch_vccz .LBB0_697

; __device__ __forceinline__ u32x2 pack4u(f32x4 a) { u32x2 w = {cvt_pk_bf16(a[0], a[1]), cvt_pk_bf16(a[2], a[3])}; return w; }
;     __device__ __forceinline__ void operator()(const AccT& acc, const Unit& u, int wr, int wc, int fr, int fq) const {
;     ...
;                     if (g8 < 8) {
;                         const int i0 = 4 * g8;
;                         const f32x4 cs = *(const f32x4*)(COS + (size_t)row * 32 + i0), sn = *(const f32x4*)(SIN + (size_t)row * 32 + i0);
;                         const f32x4 o1 = v0 * cs - v1 * sn, o2 = v1 * cs + v0 * sn;
;                         const u32x2 w1 = pack4u(o1), w2 = pack4u(o2);
;                         const int b = row / SEQ, t = row % SEQ;
;                         bf16_t* kp = Kb + ((size_t)(b * NH) * SEQ + t) * DQK + 128 + i0;
; #pragma unroll
;                         for (int h = 0; h < NH; ++h) { *(u32x2*)(kp + (size_t)h * SEQ * DQK) = w1; *(u32x2*)(kp + (size_t)h * SEQ * DQK + 32) = w2; }
.LBB0_717:
	v_ashrrev_i32_e32 v133, 31, v132
	v_lshlrev_b64 v[134:135], 7, v[132:133]
	v_lshl_add_u64 v[128:129], v[146:147], 0, v[134:135]
	v_lshl_add_u64 v[134:135], v[148:149], 0, v[134:135]
	s_waitcnt vmcnt(4)
	v_mov_b32_e32 v128, v176
	v_mov_b32_e32 v129, v177
	v_mov_b32_e32 v130, v178
	v_mov_b32_e32 v131, v179
	v_lshrrev_b32_e32 v133, 21, v133
	v_mov_b32_e32 v158, v180
	v_mov_b32_e32 v159, v181
	v_mov_b32_e32 v160, v182
	v_mov_b32_e32 v161, v183
	v_add_u32_e32 v133, v132, v133
	v_ashrrev_i32_e32 v133, 11, v133
	s_nop 0
	v_pk_mul_f32 v[134:135], v[42:43], v[160:161]
	v_pk_mul_f32 v[166:167], v[40:41], v[158:159]
	v_pk_fma_f32 v[134:135], v[46:47], v[130:131], v[134:135] neg_lo:[0,0,1] neg_hi:[0,0,1]
	v_pk_mul_f32 v[160:161], v[46:47], v[160:161]
	v_pk_mul_f32 v[158:159], v[44:45], v[158:159]
	v_pk_fma_f32 v[166:167], v[44:45], v[128:129], v[166:167] neg_lo:[0,0,1] neg_hi:[0,0,1]
	v_pk_fma_f32 v[160:161], v[42:43], v[130:131], v[160:161]
	v_pk_fma_f32 v[130:131], v[40:41], v[128:129], v[158:159]
	v_cvt_pk_bf16_f32 v129, v134, v135
	v_mul_i32_i24_e32 v134, 0x800, v133
	v_sub_u32_e32 v132, v132, v134
	v_lshlrev_b32_e32 v134, 3, v133
	v_ashrrev_i32_e32 v135, 31, v134
	v_lshlrev_b64 v[134:135], 11, v[134:135]
	v_ashrrev_i32_e32 v133, 31, v132
	v_lshl_add_u64 v[132:133], v[134:135], 0, v[132:133]
	v_mad_u64_u32 v[134:135], s[2:3], v132, s33, v[150:151]
	v_mad_i32_i24 v135, v133, s33, v135
	v_add_co_u32_e32 v132, vcc, s76, v134
	v_cvt_pk_bf16_f32 v128, v166, v167
	s_nop 0
	v_addc_co_u32_e32 v133, vcc, 0, v135, vcc
	v_cvt_pk_bf16_f32 v130, v130, v131
	v_cvt_pk_bf16_f32 v131, v160, v161
	global_store_dwordx2 v[134:135], v[128:129], off offset:256
	global_store_dwordx2 v[134:135], v[130:131], off offset:320
	global_store_dwordx2 v[132:133], v[128:129], off offset:256
	global_store_dwordx2 v[132:133], v[130:131], off offset:320
	v_add_co_u32_e32 v132, vcc, s78, v134
	s_nop 1
	v_addc_co_u32_e32 v133, vcc, 0, v135, vcc
	global_store_dwordx2 v[132:133], v[128:129], off offset:256
	global_store_dwordx2 v[132:133], v[130:131], off offset:320
	v_add_co_u32_e32 v132, vcc, s82, v134
	s_nop 1
	v_addc_co_u32_e32 v133, vcc, 0, v135, vcc
	global_store_dwordx2 v[132:133], v[128:129], off offset:256
	global_store_dwordx2 v[132:133], v[130:131], off offset:320
	v_add_co_u32_e32 v132, vcc, s90, v134
	s_nop 1
	v_addc_co_u32_e32 v133, vcc, 0, v135, vcc
	global_store_dwordx2 v[132:133], v[128:129], off offset:256
	global_store_dwordx2 v[132:133], v[130:131], off offset:320
	v_add_co_u32_e32 v132, vcc, 0x3c0000, v134
	s_nop 1
	v_addc_co_u32_e32 v133, vcc, 0, v135, vcc
	global_store_dwordx2 v[132:133], v[128:129], off offset:256
	global_store_dwordx2 v[132:133], v[130:131], off offset:320
	v_add_co_u32_e32 v132, vcc, 0x480000, v134
	s_nop 1
	v_addc_co_u32_e32 v133, vcc, 0, v135, vcc
	global_store_dwordx2 v[132:133], v[128:129], off offset:256
	global_store_dwordx2 v[132:133], v[130:131], off offset:320
	v_add_co_u32_e32 v132, vcc, 0x540000, v134
	s_nop 1
	v_addc_co_u32_e32 v133, vcc, 0, v135, vcc
	global_store_dwordx2 v[132:133], v[128:129], off offset:256
	global_store_dwordx2 v[132:133], v[130:131], off offset:320
	v_add_u32_e32 v132, 0xa0, v156
	s_and_b64 vcc, exec, s[46:47]
	s_mov_b64 s[26:27], -1
	s_cbranch_vccz .LBB0_701

; __device__ __forceinline__ u32x2 pack4u(f32x4 a) { u32x2 w = {cvt_pk_bf16(a[0], a[1]), cvt_pk_bf16(a[2], a[3])}; return w; }
;     __device__ __forceinline__ void operator()(const AccT& acc, const Unit& u, int wr, int wc, int fr, int fq) const {
;     ...
;                     if (g8 < 8) {
;                         const int i0 = 4 * g8;
;                         const f32x4 cs = *(const f32x4*)(COS + (size_t)row * 32 + i0), sn = *(const f32x4*)(SIN + (size_t)row * 32 + i0);
;                         const f32x4 o1 = v0 * cs - v1 * sn, o2 = v1 * cs + v0 * sn;
;                         const u32x2 w1 = pack4u(o1), w2 = pack4u(o2);
;                         const int b = row / SEQ, t = row % SEQ;
;                         bf16_t* kp = Kb + ((size_t)(b * NH) * SEQ + t) * DQK + 128 + i0;
; #pragma unroll
;                         for (int h = 0; h < NH; ++h) { *(u32x2*)(kp + (size_t)h * SEQ * DQK) = w1; *(u32x2*)(kp + (size_t)h * SEQ * DQK + 32) = w2; }
.LBB0_719:
	v_ashrrev_i32_e32 v133, 31, v132
	v_lshlrev_b64 v[134:135], 7, v[132:133]
	v_lshl_add_u64 v[128:129], v[146:147], 0, v[134:135]
	v_lshl_add_u64 v[134:135], v[148:149], 0, v[134:135]
	s_waitcnt vmcnt(2)
	v_mov_b32_e32 v128, v184
	v_mov_b32_e32 v129, v185
	v_mov_b32_e32 v130, v186
	v_mov_b32_e32 v131, v187
	v_lshrrev_b32_e32 v133, 21, v133
	v_mov_b32_e32 v158, v188
	v_mov_b32_e32 v159, v189
	v_mov_b32_e32 v160, v190
	v_mov_b32_e32 v161, v191
	v_add_u32_e32 v133, v132, v133
	v_ashrrev_i32_e32 v133, 11, v133
	s_nop 0
	v_pk_mul_f32 v[134:135], v[26:27], v[160:161]
	v_pk_mul_f32 v[166:167], v[24:25], v[158:159]
	v_pk_fma_f32 v[134:135], v[30:31], v[130:131], v[134:135] neg_lo:[0,0,1] neg_hi:[0,0,1]
	v_pk_mul_f32 v[160:161], v[30:31], v[160:161]
	v_pk_mul_f32 v[158:159], v[28:29], v[158:159]
	v_pk_fma_f32 v[166:167], v[28:29], v[128:129], v[166:167] neg_lo:[0,0,1] neg_hi:[0,0,1]
	v_pk_fma_f32 v[160:161], v[26:27], v[130:131], v[160:161]
	v_pk_fma_f32 v[130:131], v[24:25], v[128:129], v[158:159]
	v_cvt_pk_bf16_f32 v129, v134, v135
	v_mul_i32_i24_e32 v134, 0x800, v133
	v_sub_u32_e32 v132, v132, v134
	v_lshlrev_b32_e32 v134, 3, v133
	v_ashrrev_i32_e32 v135, 31, v134
	v_lshlrev_b64 v[134:135], 11, v[134:135]
	v_ashrrev_i32_e32 v133, 31, v132
	v_lshl_add_u64 v[132:133], v[134:135], 0, v[132:133]
	v_mad_u64_u32 v[134:135], s[2:3], v132, s33, v[150:151]
	v_mad_i32_i24 v135, v133, s33, v135
	v_add_co_u32_e32 v132, vcc, s76, v134
	v_cvt_pk_bf16_f32 v128, v166, v167
	s_nop 0
	v_addc_co_u32_e32 v133, vcc, 0, v135, vcc
	v_cvt_pk_bf16_f32 v130, v130, v131
	v_cvt_pk_bf16_f32 v131, v160, v161
	global_store_dwordx2 v[134:135], v[128:129], off offset:256
	global_store_dwordx2 v[134:135], v[130:131], off offset:320
	global_store_dwordx2 v[132:133], v[128:129], off offset:256
	global_store_dwordx2 v[132:133], v[130:131], off offset:320
	v_add_co_u32_e32 v132, vcc, s78, v134
	s_nop 1
	v_addc_co_u32_e32 v133, vcc, 0, v135, vcc
	global_store_dwordx2 v[132:133], v[128:129], off offset:256
	global_store_dwordx2 v[132:133], v[130:131], off offset:320
	v_add_co_u32_e32 v132, vcc, s82, v134
	s_nop 1
	v_addc_co_u32_e32 v133, vcc, 0, v135, vcc
	global_store_dwordx2 v[132:133], v[128:129], off offset:256
	global_store_dwordx2 v[132:133], v[130:131], off offset:320
	v_add_co_u32_e32 v132, vcc, s90, v134
	s_nop 1
	v_addc_co_u32_e32 v133, vcc, 0, v135, vcc
	global_store_dwordx2 v[132:133], v[128:129], off offset:256
	global_store_dwordx2 v[132:133], v[130:131], off offset:320
	v_add_co_u32_e32 v132, vcc, 0x3c0000, v134
	s_nop 1
	v_addc_co_u32_e32 v133, vcc, 0, v135, vcc
	global_store_dwordx2 v[132:133], v[128:129], off offset:256
	global_store_dwordx2 v[132:133], v[130:131], off offset:320
	v_add_co_u32_e32 v132, vcc, 0x480000, v134
	s_nop 1
	v_addc_co_u32_e32 v133, vcc, 0, v135, vcc
	global_store_dwordx2 v[132:133], v[128:129], off offset:256
	global_store_dwordx2 v[132:133], v[130:131], off offset:320
	v_add_co_u32_e32 v132, vcc, 0x540000, v134
	s_nop 1
	v_addc_co_u32_e32 v133, vcc, 0, v135, vcc
	global_store_dwordx2 v[132:133], v[128:129], off offset:256
	global_store_dwordx2 v[132:133], v[130:131], off offset:320
	v_add_u32_e32 v132, 0xb0, v156
	s_and_b64 vcc, exec, s[46:47]
	s_mov_b64 s[26:27], -1
	s_cbranch_vccz .LBB0_705

; __device__ __forceinline__ u32x2 pack4u(f32x4 a) { u32x2 w = {cvt_pk_bf16(a[0], a[1]), cvt_pk_bf16(a[2], a[3])}; return w; }
;     __device__ __forceinline__ void operator()(const AccT& acc, const Unit& u, int wr, int wc, int fr, int fq) const {
;     ...
;                     if (g8 < 8) {
;                         const int i0 = 4 * g8;
;                         const f32x4 cs = *(const f32x4*)(COS + (size_t)row * 32 + i0), sn = *(const f32x4*)(SIN + (size_t)row * 32 + i0);
;                         const f32x4 o1 = v0 * cs - v1 * sn, o2 = v1 * cs + v0 * sn;
;                         const u32x2 w1 = pack4u(o1), w2 = pack4u(o2);
;                         const int b = row / SEQ, t = row % SEQ;
;                         bf16_t* kp = Kb + ((size_t)(b * NH) * SEQ + t) * DQK + 128 + i0;
; #pragma unroll
;                         for (int h = 0; h < NH; ++h) { *(u32x2*)(kp + (size_t)h * SEQ * DQK) = w1; *(u32x2*)(kp + (size_t)h * SEQ * DQK + 32) = w2; }
.LBB0_721:
	v_ashrrev_i32_e32 v133, 31, v132
	v_lshlrev_b64 v[134:135], 7, v[132:133]
	v_lshl_add_u64 v[128:129], v[146:147], 0, v[134:135]
	v_lshl_add_u64 v[134:135], v[148:149], 0, v[134:135]
	s_waitcnt vmcnt(0)
	v_mov_b32_e32 v128, v192
	v_mov_b32_e32 v129, v193
	v_mov_b32_e32 v130, v194
	v_mov_b32_e32 v131, v195
	v_lshrrev_b32_e32 v133, 21, v133
	v_mov_b32_e32 v158, v196
	v_mov_b32_e32 v159, v197
	v_mov_b32_e32 v160, v198
	v_mov_b32_e32 v161, v199
	v_add_u32_e32 v133, v132, v133
	v_ashrrev_i32_e32 v133, 11, v133
	s_nop 0
	v_pk_mul_f32 v[134:135], v[10:11], v[160:161]
	v_pk_mul_f32 v[166:167], v[8:9], v[158:159]
	v_pk_fma_f32 v[134:135], v[14:15], v[130:131], v[134:135] neg_lo:[0,0,1] neg_hi:[0,0,1]
	v_pk_mul_f32 v[160:161], v[14:15], v[160:161]
	v_pk_mul_f32 v[158:159], v[12:13], v[158:159]
	v_pk_fma_f32 v[166:167], v[12:13], v[128:129], v[166:167] neg_lo:[0,0,1] neg_hi:[0,0,1]
	v_pk_fma_f32 v[160:161], v[10:11], v[130:131], v[160:161]
	v_pk_fma_f32 v[130:131], v[8:9], v[128:129], v[158:159]
	v_cvt_pk_bf16_f32 v129, v134, v135
	v_mul_i32_i24_e32 v134, 0x800, v133
	v_sub_u32_e32 v132, v132, v134
	v_lshlrev_b32_e32 v134, 3, v133
	v_ashrrev_i32_e32 v135, 31, v134
	v_lshlrev_b64 v[134:135], 11, v[134:135]
	v_ashrrev_i32_e32 v133, 31, v132
	v_lshl_add_u64 v[132:133], v[134:135], 0, v[132:133]
	v_mad_u64_u32 v[134:135], s[2:3], v132, s33, v[150:151]
	v_mad_i32_i24 v135, v133, s33, v135
	v_add_co_u32_e32 v132, vcc, s76, v134
	v_cvt_pk_bf16_f32 v128, v166, v167
	s_nop 0
	v_addc_co_u32_e32 v133, vcc, 0, v135, vcc
	v_cvt_pk_bf16_f32 v130, v130, v131
	v_cvt_pk_bf16_f32 v131, v160, v161
	global_store_dwordx2 v[134:135], v[128:129], off offset:256
	global_store_dwordx2 v[134:135], v[130:131], off offset:320
	global_store_dwordx2 v[132:133], v[128:129], off offset:256
	global_store_dwordx2 v[132:133], v[130:131], off offset:320
	v_add_co_u32_e32 v132, vcc, s78, v134
	s_nop 1
	v_addc_co_u32_e32 v133, vcc, 0, v135, vcc
	global_store_dwordx2 v[132:133], v[128:129], off offset:256
	global_store_dwordx2 v[132:133], v[130:131], off offset:320
	v_add_co_u32_e32 v132, vcc, s82, v134
	s_nop 1
	v_addc_co_u32_e32 v133, vcc, 0, v135, vcc
	global_store_dwordx2 v[132:133], v[128:129], off offset:256
	global_store_dwordx2 v[132:133], v[130:131], off offset:320
	v_add_co_u32_e32 v132, vcc, s90, v134
	s_nop 1
	v_addc_co_u32_e32 v133, vcc, 0, v135, vcc
	global_store_dwordx2 v[132:133], v[128:129], off offset:256
	global_store_dwordx2 v[132:133], v[130:131], off offset:320
	v_add_co_u32_e32 v132, vcc, 0x3c0000, v134
	s_nop 1
	v_addc_co_u32_e32 v133, vcc, 0, v135, vcc
	global_store_dwordx2 v[132:133], v[128:129], off offset:256
	global_store_dwordx2 v[132:133], v[130:131], off offset:320
	v_add_co_u32_e32 v132, vcc, 0x480000, v134
	s_nop 1
	v_addc_co_u32_e32 v133, vcc, 0, v135, vcc
	global_store_dwordx2 v[132:133], v[128:129], off offset:256
	global_store_dwordx2 v[132:133], v[130:131], off offset:320
	v_add_co_u32_e32 v132, vcc, 0x540000, v134
	s_nop 1
	v_addc_co_u32_e32 v133, vcc, 0, v135, vcc
	global_store_dwordx2 v[132:133], v[128:129], off offset:256
	global_store_dwordx2 v[132:133], v[130:131], off offset:320
